# G3: gMLP first-stage loads issued at the loop header ahead of the token-statistics load and barrier (on top of G2b+P3SP)
# speedup vs baseline: 1.0055x; 1.0001x over previous
; __device__ __forceinline__ float bf_lo(unsigned w) { return __uint_as_float(w << 16); }
; __device__ __forceinline__ float bf_hi(unsigned w) { return __uint_as_float(w & 0xffff0000u); }
; __device__ __forceinline__ bf16_t f2bf(float f) { return (bf16_t)(cvt_pk_bf16(f, 0.f) & 0xffffu); }
; __global__ void __launch_bounds__(NTHR, 2) mega_fwd(Args a) {
;     ...
;                     const int tok = tid >> 2, cq = (tid & 3) * 32; const float mean = st[2 * tok], rstd = st[2 * tok + 1];
;                     const bf16_t* vp = PB + ((size_t)(16 + gi) * T + r0 + tok) * 128 + cq;
; #pragma unroll
;                     for (int i = 0; i < 4; ++i) { const u32x4 w = *(const u32x4*)(vp + 8 * i);
; #pragma unroll
;                         for (int j = 0; j < 4; ++j) { const int c = cq + 8 * i + 2 * j;
;                             const float x0 = gelu_tanh(bf_lo(w[j])), x1 = gelu_tanh(bf_hi(w[j]));
;                             vT[c * 136 + tok] = f2bf((x0 - mean) * rstd * lng[gi * 128 + c] + lnb[gi * 128 + c]);
;                             vT[(c + 1) * 136 + tok] = f2bf((x1 - mean) * rstd * lng[gi * 128 + c + 1] + lnb[gi * 128 + c + 1]); } }
;     ...
;                     const bf16_t* wrow = wtril + ((size_t)(l * 4 + gi) * 128 + 16 * wave + (lane & 15)) * 128 + 8 * (lane >> 4);
; #pragma unroll
;                     for (int kk = 0; kk < 4; ++kk) { const bf16x8 av = *(const bf16x8*)(wrow + kk * 32);
; #pragma unroll
;                         for (int ct = 0; ct < 8; ++ct) { const bf16x8 bv = *(const bf16x8*)(vT + (ct * 16 + (lane & 15)) * 136 + kk * 32 + 8 * (lane >> 4));
;                             acc[ct] = __builtin_amdgcn_mfma_f32_16x16x32_bf16(av, bv, acc[ct], 0, 0, 0); } }
; #pragma unroll
;                     for (int j = 0; j < 4; ++j) { const int t = 16 * wave + 4 * (lane >> 4) + j; const float bt = bs[gi * 128 + t];
; #pragma unroll
;                         for (int ct = 0; ct < 8; ++ct) svL[t * 132 + ct * 16 + (lane & 15)] = acc[ct][j] + bt; }
;                 }
;                 __syncthreads();
;                 {
;                     const int c0 = (tid & 15) * 8;
; #pragma unroll
;                     for (int i = 0; i < 4; ++i) { const int t = 32 * i + (tid >> 4);
;                         const u32x4 uw = *(const u32x4*)(PB + ((size_t)(12 + gi) * T + r0 + t) * 128 + c0);
.LBB0_518:
	s_or_b64 exec, exec, s[14:15]
	s_and_b32 s26, s22, 3
	s_lshl_b32 s14, s26, 14
	s_or_b32 s10, s14, 0x40000
	s_ashr_i32 s15, s23, 31
	s_add_u32 s34, s10, s23
	s_addc_u32 s35, 0, s15
	v_lshl_add_u64 v[4:5], s[34:35], 0, v[36:37]
	v_lshlrev_b64 v[4:5], 8, v[4:5]
	v_lshl_add_u64 v[10:11], v[38:39], 0, v[4:5]
	s_waitcnt lgkmcnt(0)
	s_barrier
	ds_read_b64 v[8:9], v57 offset:40960
	s_lshl_b32 s27, s26, 7
	s_or_b32 s30, s27, s16
	s_or_b32 s10, s14, 0x30000
	s_add_u32 s14, s10, s23
	s_addc_u32 s15, 0, s15
	s_add_i32 s22, s22, s13
	s_add_i32 s17, s17, s33
	s_waitcnt vmcnt(0)
	v_mov_b64_e32 v[4:5], v[96:97]
	v_mov_b64_e32 v[6:7], v[98:99]
	v_lshl_add_u64 v[114:115], v[40:41], 0, s[30:31]
	v_lshlrev_b64 v[114:115], 8, v[114:115]
	v_lshl_add_u64 v[114:115], v[42:43], 0, v[114:115]
	global_load_dwordx4 v[180:183], v[114:115], off
	global_load_dwordx4 v[184:187], v[114:115], off offset:64
	global_load_dwordx4 v[188:191], v[114:115], off offset:128
	global_load_dwordx4 v[192:195], v[114:115], off offset:192
	v_lshl_add_u64 v[214:215], s[14:15], 0, v[44:45]
	v_lshlrev_b64 v[214:215], 8, v[214:215]
	v_lshl_add_u64 v[214:215], v[46:47], 0, v[214:215]
	global_load_dwordx4 v[218:221], v[214:215], off
	v_lshl_add_u64 v[214:215], s[14:15], 0, v[48:49]
	v_lshlrev_b64 v[214:215], 8, v[214:215]
	v_lshl_add_u64 v[214:215], v[46:47], 0, v[214:215]
	global_load_dwordx4 v[222:225], v[214:215], off
	v_lshl_add_u64 v[214:215], s[14:15], 0, v[50:51]
	v_lshlrev_b64 v[214:215], 8, v[214:215]
	v_lshl_add_u64 v[214:215], v[46:47], 0, v[214:215]
	global_load_dwordx4 v[226:229], v[214:215], off
	v_lshl_add_u64 v[214:215], s[14:15], 0, v[52:53]
	v_lshlrev_b64 v[214:215], 8, v[214:215]
	v_lshl_add_u64 v[214:215], v[46:47], 0, v[214:215]
	global_load_dwordx4 v[230:233], v[214:215], off
	v_lshlrev_b32_e32 v12, 16, v4
	v_mul_f32_e32 v13, 0x3d372713, v12
	v_mul_f32_e32 v13, v13, v12
	v_fma_f32 v13, v13, v12, v12
	v_mul_f32_e32 v13, 0x3f4c422a, v13
	v_mul_f32_e32 v13, -2.0, v13
	v_mul_f32_e32 v13, 0x3fb8aa3b, v13
	v_exp_f32_e32 v13, v13
	v_and_b32_e32 v4, 0xffff0000, v4
	v_mul_f32_e32 v14, 0x3d372713, v4
	v_mul_f32_e32 v14, v14, v4
	v_add_f32_e32 v13, 1.0, v13
	v_rcp_f32_e32 v13, v13
	v_fma_f32 v14, v14, v4, v4
	v_mul_f32_e32 v14, 0x3f4c422a, v14
	v_mul_f32_e32 v14, -2.0, v14
	s_waitcnt lgkmcnt(0)
	v_fma_f32 v12, v13, v12, -v8
	v_mul_f32_e32 v13, v9, v12
	v_or_b32_e32 v12, s27, v56
	v_lshlrev_b32_e32 v12, 2, v12
	v_mov_b32_e32 v15, v116
	v_mov_b32_e32 v16, v148
	v_mul_f32_e32 v14, 0x3fb8aa3b, v14
	v_exp_f32_e32 v14, v14
	v_fmac_f32_e32 v16, v13, v15
	v_add_f32_e32 v14, 1.0, v14
	v_rcp_f32_e32 v14, v14
	v_cvt_pk_bf16_f32 v13, v16, v3
	ds_write_b16 v60, v13
	v_fma_f32 v4, v14, v4, -v8
	v_mov_b32_e32 v13, v117
	v_mov_b32_e32 v14, v149
	v_mul_f32_e32 v4, v9, v4
	v_fmac_f32_e32 v14, v4, v13
	v_cvt_pk_bf16_f32 v4, v14, v3
	ds_write_b16 v61, v4 offset:272
	v_lshlrev_b32_e32 v4, 16, v5
	v_mul_f32_e32 v13, 0x3d372713, v4
	v_mul_f32_e32 v13, v13, v4
	v_fma_f32 v13, v13, v4, v4
	v_mul_f32_e32 v13, 0x3f4c422a, v13
	v_mul_f32_e32 v13, -2.0, v13
	v_mul_f32_e32 v13, 0x3fb8aa3b, v13
	v_exp_f32_e32 v13, v13
	v_and_b32_e32 v5, 0xffff0000, v5
	v_mul_f32_e32 v14, 0x3d372713, v5
	v_mul_f32_e32 v14, v14, v5
	v_add_f32_e32 v13, 1.0, v13
	v_rcp_f32_e32 v13, v13
	v_fma_f32 v14, v14, v5, v5
	v_mul_f32_e32 v14, 0x3f4c422a, v14
	v_mul_f32_e32 v14, -2.0, v14
	v_fma_f32 v4, v13, v4, -v8
	v_mov_b32_e32 v13, v118
	v_mov_b32_e32 v15, v150
	v_mul_f32_e32 v14, 0x3fb8aa3b, v14
	v_exp_f32_e32 v14, v14
	v_mul_f32_e32 v4, v9, v4
	v_add_f32_e32 v14, 1.0, v14
	v_rcp_f32_e32 v14, v14
	v_fmac_f32_e32 v15, v4, v13
	v_cvt_pk_bf16_f32 v4, v15, v3
	ds_write_b16 v61, v4 offset:544
	v_fma_f32 v4, v14, v5, -v8
	v_mov_b32_e32 v5, v119
	v_mov_b32_e32 v13, v151
	v_mul_f32_e32 v4, v9, v4
	v_fmac_f32_e32 v13, v4, v5
	v_cvt_pk_bf16_f32 v4, v13, v3
	ds_write_b16 v62, v4 offset:272
	v_lshlrev_b32_e32 v4, 16, v6
	v_mul_f32_e32 v5, 0x3d372713, v4
	v_mul_f32_e32 v5, v5, v4
	v_fma_f32 v5, v5, v4, v4
	v_mul_f32_e32 v5, 0x3f4c422a, v5
	v_mul_f32_e32 v5, -2.0, v5
	v_mul_f32_e32 v5, 0x3fb8aa3b, v5
	v_exp_f32_e32 v5, v5
	v_and_b32_e32 v6, 0xffff0000, v6
	v_mul_f32_e32 v13, 0x3d372713, v6
	v_mul_f32_e32 v13, v13, v6
	v_add_f32_e32 v5, 1.0, v5
	v_rcp_f32_e32 v5, v5
	v_fma_f32 v13, v13, v6, v6
	v_mul_f32_e32 v13, 0x3f4c422a, v13
	v_mul_f32_e32 v13, -2.0, v13
	v_fma_f32 v4, v5, v4, -v8
	v_mov_b32_e32 v5, v120
	v_mov_b32_e32 v14, v152
	v_mul_f32_e32 v13, 0x3fb8aa3b, v13
	v_exp_f32_e32 v13, v13
	v_mul_f32_e32 v4, v9, v4
	v_add_f32_e32 v13, 1.0, v13
	v_rcp_f32_e32 v13, v13
	v_fmac_f32_e32 v14, v4, v5
	v_cvt_pk_bf16_f32 v4, v14, v3
	ds_write_b16 v62, v4 offset:544
	v_fma_f32 v4, v13, v6, -v8
	v_mov_b32_e32 v5, v121
	v_mov_b32_e32 v6, v153
	v_mul_f32_e32 v4, v9, v4
	v_fmac_f32_e32 v6, v4, v5
	v_cvt_pk_bf16_f32 v4, v6, v3
	ds_write_b16 v63, v4 offset:272
	v_lshlrev_b32_e32 v4, 16, v7
	v_mul_f32_e32 v5, 0x3d372713, v4
	v_mul_f32_e32 v5, v5, v4
	v_fma_f32 v5, v5, v4, v4
	v_mul_f32_e32 v5, 0x3f4c422a, v5
	v_mul_f32_e32 v5, -2.0, v5
	v_mul_f32_e32 v5, 0x3fb8aa3b, v5
	v_exp_f32_e32 v5, v5
	v_and_b32_e32 v6, 0xffff0000, v7
	v_mul_f32_e32 v7, 0x3d372713, v6
	v_mul_f32_e32 v7, v7, v6
	v_add_f32_e32 v5, 1.0, v5
	v_rcp_f32_e32 v5, v5
	v_fma_f32 v7, v7, v6, v6
	v_mul_f32_e32 v7, 0x3f4c422a, v7
	v_mul_f32_e32 v7, -2.0, v7
	v_fma_f32 v4, v5, v4, -v8
	v_mov_b32_e32 v5, v122
	v_mov_b32_e32 v13, v154
	v_mul_f32_e32 v7, 0x3fb8aa3b, v7
	v_exp_f32_e32 v7, v7
	v_mul_f32_e32 v4, v9, v4
	v_add_f32_e32 v7, 1.0, v7
	v_rcp_f32_e32 v7, v7
	v_fmac_f32_e32 v13, v4, v5
	v_cvt_pk_bf16_f32 v4, v13, v3
	ds_write_b16 v63, v4 offset:544
	v_fma_f32 v4, v7, v6, -v8
	v_mov_b32_e32 v5, v123
; __device__ __forceinline__ float bf_lo(unsigned w) { return __uint_as_float(w << 16); }
; __device__ __forceinline__ float bf_hi(unsigned w) { return __uint_as_float(w & 0xffff0000u); }
; __device__ __forceinline__ bf16_t f2bf(float f) { return (bf16_t)(cvt_pk_bf16(f, 0.f) & 0xffffu); }
; __global__ void __launch_bounds__(NTHR, 2) mega_fwd(Args a) {
;     ...
;                     for (int i = 0; i < 4; ++i) { const u32x4 w = *(const u32x4*)(vp + 8 * i);
; #pragma unroll
;                         for (int j = 0; j < 4; ++j) { const int c = cq + 8 * i + 2 * j;
;                             const float x0 = gelu_tanh(bf_lo(w[j])), x1 = gelu_tanh(bf_hi(w[j]));
;                             vT[c * 136 + tok] = f2bf((x0 - mean) * rstd * lng[gi * 128 + c] + lnb[gi * 128 + c]);
;                             vT[(c + 1) * 136 + tok] = f2bf((x1 - mean) * rstd * lng[gi * 128 + c + 1] + lnb[gi * 128 + c + 1]); } }
	v_mov_b32_e32 v6, v155
	v_mul_f32_e32 v4, v9, v4
	v_fmac_f32_e32 v6, v4, v5
	v_cvt_pk_bf16_f32 v4, v6, v3
	ds_write_b16 v64, v4 offset:272
	v_mov_b64_e32 v[4:5], v[100:101]
	v_mov_b64_e32 v[6:7], v[102:103]
	v_lshlrev_b32_e32 v13, 16, v4
	v_mul_f32_e32 v14, 0x3d372713, v13
	v_mul_f32_e32 v14, v14, v13
	v_fma_f32 v14, v14, v13, v13
	v_mul_f32_e32 v14, 0x3f4c422a, v14
	v_mul_f32_e32 v14, -2.0, v14
	v_mul_f32_e32 v14, 0x3fb8aa3b, v14
	v_exp_f32_e32 v14, v14
	v_and_b32_e32 v4, 0xffff0000, v4
	v_mul_f32_e32 v15, 0x3d372713, v4
	v_mul_f32_e32 v15, v15, v4
	v_add_f32_e32 v14, 1.0, v14
	v_rcp_f32_e32 v14, v14
	v_fma_f32 v15, v15, v4, v4
	v_mul_f32_e32 v15, 0x3f4c422a, v15
	v_mul_f32_e32 v15, -2.0, v15
	v_fma_f32 v13, v14, v13, -v8
	v_mov_b32_e32 v14, v124
	v_mov_b32_e32 v16, v156
	v_mul_f32_e32 v13, v9, v13
	v_mul_f32_e32 v15, 0x3fb8aa3b, v15
	v_exp_f32_e32 v15, v15
	v_fmac_f32_e32 v16, v13, v14
	v_cvt_pk_bf16_f32 v13, v16, v3
	ds_write_b16 v64, v13 offset:544
	v_mov_b32_e32 v13, v125
	v_mov_b32_e32 v14, v157
	v_add_f32_e32 v15, 1.0, v15
	v_rcp_f32_e32 v15, v15
	s_nop 0
	v_fma_f32 v4, v15, v4, -v8
	v_mul_f32_e32 v4, v9, v4
	v_fmac_f32_e32 v14, v4, v13
	v_cvt_pk_bf16_f32 v4, v14, v3
	ds_write_b16 v65, v4 offset:272
	v_lshlrev_b32_e32 v4, 16, v5
	v_mul_f32_e32 v13, 0x3d372713, v4
	v_mul_f32_e32 v13, v13, v4
	v_fma_f32 v13, v13, v4, v4
	v_mul_f32_e32 v13, 0x3f4c422a, v13
	v_mul_f32_e32 v13, -2.0, v13
	v_mul_f32_e32 v13, 0x3fb8aa3b, v13
	v_exp_f32_e32 v13, v13
	v_and_b32_e32 v5, 0xffff0000, v5
	v_mul_f32_e32 v14, 0x3d372713, v5
	v_mul_f32_e32 v14, v14, v5
	v_add_f32_e32 v13, 1.0, v13
	v_rcp_f32_e32 v13, v13
	v_fma_f32 v14, v14, v5, v5
	v_mul_f32_e32 v14, 0x3f4c422a, v14
	v_mul_f32_e32 v14, -2.0, v14
	v_fma_f32 v4, v13, v4, -v8
	v_mov_b32_e32 v13, v126
	v_mov_b32_e32 v15, v158
	v_mul_f32_e32 v14, 0x3fb8aa3b, v14
	v_exp_f32_e32 v14, v14
	v_mul_f32_e32 v4, v9, v4
	v_add_f32_e32 v14, 1.0, v14
	v_rcp_f32_e32 v14, v14
	v_fmac_f32_e32 v15, v4, v13
	v_cvt_pk_bf16_f32 v4, v15, v3
	ds_write_b16 v65, v4 offset:544
	v_fma_f32 v4, v14, v5, -v8
	v_mov_b32_e32 v5, v127
	v_mov_b32_e32 v13, v159
	v_mul_f32_e32 v4, v9, v4
	v_fmac_f32_e32 v13, v4, v5
	v_cvt_pk_bf16_f32 v4, v13, v3
	ds_write_b16 v66, v4 offset:272
	v_lshlrev_b32_e32 v4, 16, v6
	v_mul_f32_e32 v5, 0x3d372713, v4
	v_mul_f32_e32 v5, v5, v4
	v_fma_f32 v5, v5, v4, v4
	v_mul_f32_e32 v5, 0x3f4c422a, v5
	v_mul_f32_e32 v5, -2.0, v5
	v_mul_f32_e32 v5, 0x3fb8aa3b, v5
	v_exp_f32_e32 v5, v5
	v_and_b32_e32 v6, 0xffff0000, v6
	v_mul_f32_e32 v13, 0x3d372713, v6
	v_mul_f32_e32 v13, v13, v6
	v_add_f32_e32 v5, 1.0, v5
	v_rcp_f32_e32 v5, v5
	v_fma_f32 v13, v13, v6, v6
	v_mul_f32_e32 v13, 0x3f4c422a, v13
	v_mul_f32_e32 v13, -2.0, v13
	v_fma_f32 v4, v5, v4, -v8
	v_mov_b32_e32 v5, v128
	v_mov_b32_e32 v14, v160
	v_mul_f32_e32 v13, 0x3fb8aa3b, v13
	v_exp_f32_e32 v13, v13
	v_mul_f32_e32 v4, v9, v4
	v_add_f32_e32 v13, 1.0, v13
	v_rcp_f32_e32 v13, v13
	v_fmac_f32_e32 v14, v4, v5
	v_cvt_pk_bf16_f32 v4, v14, v3
	ds_write_b16 v66, v4 offset:544
	v_fma_f32 v4, v13, v6, -v8
	v_mov_b32_e32 v5, v129
	v_mov_b32_e32 v6, v161
	v_mul_f32_e32 v4, v9, v4
	v_fmac_f32_e32 v6, v4, v5
	v_cvt_pk_bf16_f32 v4, v6, v3
	ds_write_b16 v67, v4 offset:272
	v_lshlrev_b32_e32 v4, 16, v7
	v_mul_f32_e32 v5, 0x3d372713, v4
	v_mul_f32_e32 v5, v5, v4
	v_fma_f32 v5, v5, v4, v4
	v_mul_f32_e32 v5, 0x3f4c422a, v5
	v_mul_f32_e32 v5, -2.0, v5
	v_mul_f32_e32 v5, 0x3fb8aa3b, v5
	v_exp_f32_e32 v5, v5
	v_and_b32_e32 v6, 0xffff0000, v7
	v_mul_f32_e32 v7, 0x3d372713, v6
	v_mul_f32_e32 v7, v7, v6
	v_add_f32_e32 v5, 1.0, v5
	v_rcp_f32_e32 v5, v5
	v_fma_f32 v7, v7, v6, v6
	v_mul_f32_e32 v7, 0x3f4c422a, v7
	v_mul_f32_e32 v7, -2.0, v7
	v_fma_f32 v4, v5, v4, -v8
	v_mov_b32_e32 v5, v130
	v_mov_b32_e32 v13, v162
	v_mul_f32_e32 v7, 0x3fb8aa3b, v7
	v_exp_f32_e32 v7, v7
	v_mul_f32_e32 v4, v9, v4
	v_add_f32_e32 v7, 1.0, v7
	v_rcp_f32_e32 v7, v7
	v_fmac_f32_e32 v13, v4, v5
	v_cvt_pk_bf16_f32 v4, v13, v3
	ds_write_b16 v67, v4 offset:544
	v_fma_f32 v4, v7, v6, -v8
	v_mov_b32_e32 v5, v131
	v_mov_b32_e32 v6, v163
	v_mul_f32_e32 v4, v9, v4
	v_fmac_f32_e32 v6, v4, v5
	v_cvt_pk_bf16_f32 v4, v6, v3
	ds_write_b16 v68, v4 offset:272
	v_mov_b64_e32 v[4:5], v[104:105]
	v_mov_b64_e32 v[6:7], v[106:107]
	v_lshlrev_b32_e32 v13, 16, v4
	v_mul_f32_e32 v14, 0x3d372713, v13
	v_mul_f32_e32 v14, v14, v13
	v_fma_f32 v14, v14, v13, v13
	v_mul_f32_e32 v14, 0x3f4c422a, v14
	v_mul_f32_e32 v14, -2.0, v14
	v_mul_f32_e32 v14, 0x3fb8aa3b, v14
	v_exp_f32_e32 v14, v14
	v_and_b32_e32 v4, 0xffff0000, v4
	v_mul_f32_e32 v15, 0x3d372713, v4
	v_mul_f32_e32 v15, v15, v4
	v_add_f32_e32 v14, 1.0, v14
	v_rcp_f32_e32 v14, v14
	v_fma_f32 v15, v15, v4, v4
	v_mul_f32_e32 v15, 0x3f4c422a, v15
	v_mul_f32_e32 v15, -2.0, v15
	v_fma_f32 v13, v14, v13, -v8
	v_mov_b32_e32 v14, v132
	v_mov_b32_e32 v16, v164
	v_mul_f32_e32 v13, v9, v13
	v_mul_f32_e32 v15, 0x3fb8aa3b, v15
	v_exp_f32_e32 v15, v15
	v_fmac_f32_e32 v16, v13, v14
	v_cvt_pk_bf16_f32 v13, v16, v3
	ds_write_b16 v68, v13 offset:544
	v_mov_b32_e32 v13, v133
	v_mov_b32_e32 v14, v165
	v_add_f32_e32 v15, 1.0, v15
	v_rcp_f32_e32 v15, v15
	s_nop 0
	v_fma_f32 v4, v15, v4, -v8
	v_mul_f32_e32 v4, v9, v4
	v_fmac_f32_e32 v14, v4, v13
	v_cvt_pk_bf16_f32 v4, v14, v3
	ds_write_b16 v69, v4 offset:272
	v_lshlrev_b32_e32 v4, 16, v5
	v_mul_f32_e32 v13, 0x3d372713, v4
	v_mul_f32_e32 v13, v13, v4
	v_fma_f32 v13, v13, v4, v4
	v_mul_f32_e32 v13, 0x3f4c422a, v13
	v_mul_f32_e32 v13, -2.0, v13
	v_mul_f32_e32 v13, 0x3fb8aa3b, v13
	v_exp_f32_e32 v13, v13
	v_and_b32_e32 v5, 0xffff0000, v5
	v_mul_f32_e32 v14, 0x3d372713, v5
	v_mul_f32_e32 v14, v14, v5
	v_add_f32_e32 v13, 1.0, v13
	v_rcp_f32_e32 v13, v13
; __device__ __forceinline__ float bf_lo(unsigned w) { return __uint_as_float(w << 16); }
; __device__ __forceinline__ float bf_hi(unsigned w) { return __uint_as_float(w & 0xffff0000u); }
; __device__ __forceinline__ bf16_t f2bf(float f) { return (bf16_t)(cvt_pk_bf16(f, 0.f) & 0xffffu); }
; __global__ void __launch_bounds__(NTHR, 2) mega_fwd(Args a) {
;     ...
;                     for (int i = 0; i < 4; ++i) { const u32x4 w = *(const u32x4*)(vp + 8 * i);
; #pragma unroll
;                         for (int j = 0; j < 4; ++j) { const int c = cq + 8 * i + 2 * j;
;                             const float x0 = gelu_tanh(bf_lo(w[j])), x1 = gelu_tanh(bf_hi(w[j]));
;                             vT[c * 136 + tok] = f2bf((x0 - mean) * rstd * lng[gi * 128 + c] + lnb[gi * 128 + c]);
;                             vT[(c + 1) * 136 + tok] = f2bf((x1 - mean) * rstd * lng[gi * 128 + c + 1] + lnb[gi * 128 + c + 1]); } }
;     ...
;                     const bf16_t* wrow = wtril + ((size_t)(l * 4 + gi) * 128 + 16 * wave + (lane & 15)) * 128 + 8 * (lane >> 4);
	v_fma_f32 v14, v14, v5, v5
	v_mul_f32_e32 v14, 0x3f4c422a, v14
	v_mul_f32_e32 v14, -2.0, v14
	v_fma_f32 v4, v13, v4, -v8
	v_mov_b32_e32 v13, v134
	v_mov_b32_e32 v15, v166
	v_mul_f32_e32 v14, 0x3fb8aa3b, v14
	v_exp_f32_e32 v14, v14
	v_mul_f32_e32 v4, v9, v4
	v_add_f32_e32 v14, 1.0, v14
	v_rcp_f32_e32 v14, v14
	v_fmac_f32_e32 v15, v4, v13
	v_cvt_pk_bf16_f32 v4, v15, v3
	ds_write_b16 v69, v4 offset:544
	v_fma_f32 v4, v14, v5, -v8
	v_mov_b32_e32 v5, v135
	v_mov_b32_e32 v13, v167
	v_mul_f32_e32 v4, v9, v4
	v_fmac_f32_e32 v13, v4, v5
	v_cvt_pk_bf16_f32 v4, v13, v3
	ds_write_b16 v70, v4 offset:272
	v_lshlrev_b32_e32 v4, 16, v6
	v_mul_f32_e32 v5, 0x3d372713, v4
	v_mul_f32_e32 v5, v5, v4
	v_fma_f32 v5, v5, v4, v4
	v_mul_f32_e32 v5, 0x3f4c422a, v5
	v_mul_f32_e32 v5, -2.0, v5
	v_mul_f32_e32 v5, 0x3fb8aa3b, v5
	v_exp_f32_e32 v5, v5
	v_and_b32_e32 v6, 0xffff0000, v6
	v_mul_f32_e32 v13, 0x3d372713, v6
	v_mul_f32_e32 v13, v13, v6
	v_add_f32_e32 v5, 1.0, v5
	v_rcp_f32_e32 v5, v5
	v_fma_f32 v13, v13, v6, v6
	v_mul_f32_e32 v13, 0x3f4c422a, v13
	v_mul_f32_e32 v13, -2.0, v13
	v_fma_f32 v4, v5, v4, -v8
	v_mov_b32_e32 v5, v136
	v_mov_b32_e32 v14, v168
	v_mul_f32_e32 v13, 0x3fb8aa3b, v13
	v_exp_f32_e32 v13, v13
	v_mul_f32_e32 v4, v9, v4
	v_add_f32_e32 v13, 1.0, v13
	v_rcp_f32_e32 v13, v13
	v_fmac_f32_e32 v14, v4, v5
	v_cvt_pk_bf16_f32 v4, v14, v3
	ds_write_b16 v70, v4 offset:544
	v_fma_f32 v4, v13, v6, -v8
	v_mov_b32_e32 v5, v137
	v_mov_b32_e32 v6, v169
	v_mul_f32_e32 v4, v9, v4
	v_fmac_f32_e32 v6, v4, v5
	v_cvt_pk_bf16_f32 v4, v6, v3
	ds_write_b16 v71, v4 offset:272
	v_lshlrev_b32_e32 v4, 16, v7
	v_mul_f32_e32 v5, 0x3d372713, v4
	v_mul_f32_e32 v5, v5, v4
	v_fma_f32 v5, v5, v4, v4
	v_mul_f32_e32 v5, 0x3f4c422a, v5
	v_mul_f32_e32 v5, -2.0, v5
	v_mul_f32_e32 v5, 0x3fb8aa3b, v5
	v_exp_f32_e32 v5, v5
	v_and_b32_e32 v6, 0xffff0000, v7
	v_mul_f32_e32 v7, 0x3d372713, v6
	v_mul_f32_e32 v7, v7, v6
	v_add_f32_e32 v5, 1.0, v5
	v_rcp_f32_e32 v5, v5
	v_fma_f32 v7, v7, v6, v6
	v_mul_f32_e32 v7, 0x3f4c422a, v7
	v_mul_f32_e32 v7, -2.0, v7
	v_fma_f32 v4, v5, v4, -v8
	v_mov_b32_e32 v5, v138
	v_mov_b32_e32 v13, v170
	v_mul_f32_e32 v7, 0x3fb8aa3b, v7
	v_exp_f32_e32 v7, v7
	v_mul_f32_e32 v4, v9, v4
	v_add_f32_e32 v7, 1.0, v7
	v_rcp_f32_e32 v7, v7
	v_fmac_f32_e32 v13, v4, v5
	v_cvt_pk_bf16_f32 v4, v13, v3
	ds_write_b16 v71, v4 offset:544
	v_fma_f32 v4, v7, v6, -v8
	v_mov_b32_e32 v5, v139
	v_mov_b32_e32 v6, v171
	v_mul_f32_e32 v4, v9, v4
	v_fmac_f32_e32 v6, v4, v5
	v_cvt_pk_bf16_f32 v4, v6, v3
	ds_write_b16 v72, v4 offset:272
	v_mov_b64_e32 v[4:5], v[108:109]
	v_mov_b64_e32 v[6:7], v[110:111]
	v_lshlrev_b32_e32 v10, 16, v4
	v_mul_f32_e32 v11, 0x3d372713, v10
	v_mul_f32_e32 v11, v11, v10
	v_fma_f32 v11, v11, v10, v10
	v_mul_f32_e32 v11, 0x3f4c422a, v11
	v_mul_f32_e32 v11, -2.0, v11
	v_mul_f32_e32 v11, 0x3fb8aa3b, v11
	v_exp_f32_e32 v11, v11
	v_and_b32_e32 v4, 0xffff0000, v4
	v_mul_f32_e32 v13, 0x3d372713, v4
	v_mul_f32_e32 v13, v13, v4
	v_add_f32_e32 v11, 1.0, v11
	v_rcp_f32_e32 v11, v11
	v_fma_f32 v13, v13, v4, v4
	v_mul_f32_e32 v13, 0x3f4c422a, v13
	v_mul_f32_e32 v13, -2.0, v13
	v_fma_f32 v10, v11, v10, -v8
	v_mov_b32_e32 v11, v140
	v_mov_b32_e32 v14, v172
	v_mul_f32_e32 v10, v9, v10
	v_mul_f32_e32 v13, 0x3fb8aa3b, v13
	v_exp_f32_e32 v13, v13
	v_fmac_f32_e32 v14, v10, v11
	v_cvt_pk_bf16_f32 v10, v14, v3
	ds_write_b16 v72, v10 offset:544
	v_mov_b32_e32 v10, v141
	v_mov_b32_e32 v11, v173
	v_add_f32_e32 v13, 1.0, v13
	v_rcp_f32_e32 v13, v13
	s_nop 0
	v_fma_f32 v4, v13, v4, -v8
	v_mul_f32_e32 v4, v9, v4
	v_fmac_f32_e32 v11, v4, v10
	v_cvt_pk_bf16_f32 v4, v11, v3
	ds_write_b16 v73, v4 offset:272
	v_lshlrev_b32_e32 v4, 16, v5
	v_mul_f32_e32 v10, 0x3d372713, v4
	v_mul_f32_e32 v10, v10, v4
	v_fma_f32 v10, v10, v4, v4
	v_mul_f32_e32 v10, 0x3f4c422a, v10
	v_mul_f32_e32 v10, -2.0, v10
	v_mul_f32_e32 v10, 0x3fb8aa3b, v10
	v_exp_f32_e32 v10, v10
	v_and_b32_e32 v5, 0xffff0000, v5
	v_mul_f32_e32 v11, 0x3d372713, v5
	v_mul_f32_e32 v11, v11, v5
	v_add_f32_e32 v10, 1.0, v10
	v_rcp_f32_e32 v10, v10
	v_fma_f32 v11, v11, v5, v5
	v_mul_f32_e32 v11, 0x3f4c422a, v11
	v_mul_f32_e32 v11, -2.0, v11
	v_fma_f32 v4, v10, v4, -v8
	v_mov_b32_e32 v10, v142
	v_mov_b32_e32 v13, v174
	v_mul_f32_e32 v11, 0x3fb8aa3b, v11
	v_exp_f32_e32 v11, v11
	v_mul_f32_e32 v4, v9, v4
	v_add_f32_e32 v11, 1.0, v11
	v_rcp_f32_e32 v11, v11
	v_fmac_f32_e32 v13, v4, v10
	v_cvt_pk_bf16_f32 v4, v13, v3
	ds_write_b16 v73, v4 offset:544
	v_fma_f32 v4, v11, v5, -v8
	v_mov_b32_e32 v5, v143
	v_mov_b32_e32 v10, v175
	v_mul_f32_e32 v4, v9, v4
	v_fmac_f32_e32 v10, v4, v5
	v_cvt_pk_bf16_f32 v4, v10, v3
	ds_write_b16 v74, v4 offset:272
	v_lshlrev_b32_e32 v4, 16, v6
	v_mul_f32_e32 v5, 0x3d372713, v4
	v_mul_f32_e32 v5, v5, v4
	v_fma_f32 v5, v5, v4, v4
	v_mul_f32_e32 v5, 0x3f4c422a, v5
	v_mul_f32_e32 v5, -2.0, v5
	v_mul_f32_e32 v5, 0x3fb8aa3b, v5
	v_exp_f32_e32 v5, v5
	v_and_b32_e32 v6, 0xffff0000, v6
	v_mul_f32_e32 v10, 0x3d372713, v6
	v_mul_f32_e32 v10, v10, v6
	v_add_f32_e32 v5, 1.0, v5
	v_rcp_f32_e32 v5, v5
	v_fma_f32 v10, v10, v6, v6
	v_mul_f32_e32 v10, 0x3f4c422a, v10
	v_mul_f32_e32 v10, -2.0, v10
	v_fma_f32 v4, v5, v4, -v8
	v_mov_b32_e32 v5, v144
	v_mov_b32_e32 v11, v176
	v_mul_f32_e32 v10, 0x3fb8aa3b, v10
	v_exp_f32_e32 v10, v10
	v_mul_f32_e32 v4, v9, v4
	v_add_f32_e32 v10, 1.0, v10
	v_rcp_f32_e32 v10, v10
	v_fmac_f32_e32 v11, v4, v5
	v_cvt_pk_bf16_f32 v4, v11, v3
	ds_write_b16 v74, v4 offset:544
	v_fma_f32 v4, v10, v6, -v8
	v_mov_b32_e32 v5, v145
	v_mov_b32_e32 v6, v177
	v_mul_f32_e32 v4, v9, v4
	v_fmac_f32_e32 v6, v4, v5
	v_cvt_pk_bf16_f32 v4, v6, v3
	ds_write_b16 v75, v4 offset:272
	v_lshlrev_b32_e32 v4, 16, v7
	v_mul_f32_e32 v5, 0x3d372713, v4
	v_mul_f32_e32 v5, v5, v4
	v_fma_f32 v5, v5, v4, v4
	v_mul_f32_e32 v5, 0x3f4c422a, v5
	v_mul_f32_e32 v5, -2.0, v5
	v_mul_f32_e32 v5, 0x3fb8aa3b, v5
	v_exp_f32_e32 v5, v5
	v_and_b32_e32 v6, 0xffff0000, v7
	v_mul_f32_e32 v7, 0x3d372713, v6
	v_mul_f32_e32 v7, v7, v6
	v_add_f32_e32 v5, 1.0, v5
	v_rcp_f32_e32 v5, v5
	v_fma_f32 v7, v7, v6, v6
	v_mul_f32_e32 v7, 0x3f4c422a, v7
	v_mul_f32_e32 v7, -2.0, v7
	v_fma_f32 v4, v5, v4, -v8
	v_mov_b32_e32 v5, v146
	v_mov_b32_e32 v10, v178
	v_mul_f32_e32 v7, 0x3fb8aa3b, v7
	v_exp_f32_e32 v7, v7
	v_mul_f32_e32 v4, v9, v4
	v_add_f32_e32 v7, 1.0, v7
	v_rcp_f32_e32 v7, v7
	v_fmac_f32_e32 v10, v4, v5
	v_cvt_pk_bf16_f32 v4, v10, v3
	ds_write_b16 v76, v4
	v_fma_f32 v4, v7, v6, -v8
	v_mov_b32_e32 v5, v147
	v_mov_b32_e32 v6, v179
	v_mul_f32_e32 v4, v9, v4
	v_fmac_f32_e32 v6, v4, v5
	v_cvt_pk_bf16_f32 v4, v6, v3
	ds_write_b16 v77, v4 offset:272
	v_lshl_add_u64 v[4:5], v[40:41], 0, s[30:31]
	v_lshlrev_b64 v[4:5], 8, v[4:5]
	v_lshl_add_u64 v[4:5], v[42:43], 0, v[4:5]
	s_waitcnt lgkmcnt(0)
	s_barrier
; __global__ void __launch_bounds__(NTHR, 2) mega_fwd(Args a) {
;     ...
;                 {
;                     f32x4 acc[8];
; #pragma unroll
;                     for (int ct = 0; ct < 8; ++ct) acc[ct] = (f32x4){0.f, 0.f, 0.f, 0.f};
;                     const bf16_t* wrow = wtril + ((size_t)(l * 4 + gi) * 128 + 16 * wave + (lane & 15)) * 128 + 8 * (lane >> 4);
; #pragma unroll
;                     for (int kk = 0; kk < 4; ++kk) { const bf16x8 av = *(const bf16x8*)(wrow + kk * 32);
; #pragma unroll
;                         for (int ct = 0; ct < 8; ++ct) { const bf16x8 bv = *(const bf16x8*)(vT + (ct * 16 + (lane & 15)) * 136 + kk * 32 + 8 * (lane >> 4));
;                             acc[ct] = __builtin_amdgcn_mfma_f32_16x16x32_bf16(av, bv, acc[ct], 0, 0, 0); } }
; #pragma unroll
;                     for (int j = 0; j < 4; ++j) { const int t = 16 * wave + 4 * (lane >> 4) + j; const float bt = bs[gi * 128 + t];
; #pragma unroll
;                         for (int ct = 0; ct < 8; ++ct) svL[t * 132 + ct * 16 + (lane & 15)] = acc[ct][j] + bt; }
;                 }
;                 __syncthreads();
	s_waitcnt vmcnt(0)
	v_mov_b64_e32 v[6:7], v[180:181]
	v_mov_b64_e32 v[8:9], v[182:183]
	s_nop 1
	ds_read_b128 v[10:13], v79
	ds_read_b128 v[92:95], v79 offset:64
	ds_read_b128 v[14:17], v79 offset:4352
	ds_read_b128 v[18:21], v79 offset:8704
	ds_read_b128 v[22:25], v79 offset:13056
	ds_read_b128 v[26:29], v79 offset:17408
	ds_read_b128 v[30:33], v79 offset:21760
	ds_read_b128 v[84:87], v79 offset:26112
	ds_read_b128 v[88:91], v79 offset:30464
	s_waitcnt vmcnt(0) lgkmcnt(8)
	v_mfma_f32_16x16x32_bf16 v[10:13], v[6:9], v[10:13], 0
	s_lshl_b32 s30, s26, 8
	s_cmpk_gt_i32 s22, 0x1ff
	s_waitcnt lgkmcnt(6)
	v_mfma_f32_16x16x32_bf16 v[14:17], v[6:9], v[14:17], 0
	s_waitcnt lgkmcnt(5)
	v_mfma_f32_16x16x32_bf16 v[18:21], v[6:9], v[18:21], 0
	s_waitcnt lgkmcnt(4)
	v_mfma_f32_16x16x32_bf16 v[22:25], v[6:9], v[22:25], 0
	s_waitcnt lgkmcnt(3)
	v_mfma_f32_16x16x32_bf16 v[26:29], v[6:9], v[26:29], 0
	s_waitcnt lgkmcnt(2)
	v_mfma_f32_16x16x32_bf16 v[30:33], v[6:9], v[30:33], 0
	s_waitcnt lgkmcnt(1)
	v_mfma_f32_16x16x32_bf16 v[84:87], v[6:9], v[84:87], 0
	s_waitcnt lgkmcnt(0)
	v_mfma_f32_16x16x32_bf16 v[6:9], v[6:9], v[88:91], 0
	v_mov_b64_e32 v[88:89], v[184:185]
	v_mov_b64_e32 v[90:91], v[186:187]
	s_nop 1
	s_waitcnt vmcnt(0)
	v_mfma_f32_16x16x32_bf16 v[10:13], v[88:91], v[92:95], v[10:13]
	ds_read_b128 v[92:95], v79 offset:4416
	s_waitcnt lgkmcnt(0)
	v_mfma_f32_16x16x32_bf16 v[14:17], v[88:91], v[92:95], v[14:17]
	ds_read_b128 v[92:95], v79 offset:8768
	s_waitcnt lgkmcnt(0)
	v_mfma_f32_16x16x32_bf16 v[18:21], v[88:91], v[92:95], v[18:21]
	ds_read_b128 v[92:95], v79 offset:13120
	s_waitcnt lgkmcnt(0)
	v_mfma_f32_16x16x32_bf16 v[22:25], v[88:91], v[92:95], v[22:25]
	ds_read_b128 v[92:95], v79 offset:17472
	s_waitcnt lgkmcnt(0)
	v_mfma_f32_16x16x32_bf16 v[26:29], v[88:91], v[92:95], v[26:29]
	ds_read_b128 v[92:95], v79 offset:21824
	s_waitcnt lgkmcnt(0)
	v_mfma_f32_16x16x32_bf16 v[30:33], v[88:91], v[92:95], v[30:33]
	ds_read_b128 v[92:95], v79 offset:26176
	s_waitcnt lgkmcnt(0)
	v_mfma_f32_16x16x32_bf16 v[84:87], v[88:91], v[92:95], v[84:87]
	ds_read_b128 v[92:95], v79 offset:30528
	s_waitcnt lgkmcnt(0)
	v_mfma_f32_16x16x32_bf16 v[6:9], v[88:91], v[92:95], v[6:9]
	v_mov_b64_e32 v[88:89], v[188:189]
	v_mov_b64_e32 v[90:91], v[190:191]
	s_nop 1
	ds_read_b128 v[92:95], v79 offset:128
	s_waitcnt vmcnt(0) lgkmcnt(0)
	v_mfma_f32_16x16x32_bf16 v[10:13], v[88:91], v[92:95], v[10:13]
	ds_read_b128 v[92:95], v79 offset:4480
	s_waitcnt lgkmcnt(0)
	v_mfma_f32_16x16x32_bf16 v[14:17], v[88:91], v[92:95], v[14:17]
	ds_read_b128 v[92:95], v79 offset:8832
	s_waitcnt lgkmcnt(0)
	v_mfma_f32_16x16x32_bf16 v[18:21], v[88:91], v[92:95], v[18:21]
	ds_read_b128 v[92:95], v79 offset:13184
	s_waitcnt lgkmcnt(0)
	v_mfma_f32_16x16x32_bf16 v[22:25], v[88:91], v[92:95], v[22:25]
	ds_read_b128 v[92:95], v79 offset:17536
	s_waitcnt lgkmcnt(0)
	v_mfma_f32_16x16x32_bf16 v[26:29], v[88:91], v[92:95], v[26:29]
	ds_read_b128 v[92:95], v79 offset:21888
	s_waitcnt lgkmcnt(0)
	v_mfma_f32_16x16x32_bf16 v[30:33], v[88:91], v[92:95], v[30:33]
	ds_read_b128 v[92:95], v79 offset:26240
	s_waitcnt lgkmcnt(0)
	v_mfma_f32_16x16x32_bf16 v[84:87], v[88:91], v[92:95], v[84:87]
	ds_read_b128 v[92:95], v79 offset:30592
	s_waitcnt lgkmcnt(0)
	v_mfma_f32_16x16x32_bf16 v[88:91], v[88:91], v[92:95], v[6:9]
	v_mov_b64_e32 v[92:93], v[192:193]
	v_mov_b64_e32 v[94:95], v[194:195]
	s_nop 1
	s_nop 1
	ds_read_b128 v[4:7], v79 offset:192
	s_waitcnt vmcnt(0) lgkmcnt(0)
	v_mfma_f32_16x16x32_bf16 v[4:7], v[92:95], v[4:7], v[10:13]
	s_nop 2
	ds_read_b128 v[8:11], v79 offset:4544
	s_waitcnt lgkmcnt(0)
	v_mfma_f32_16x16x32_bf16 v[8:11], v[92:95], v[8:11], v[14:17]
	s_nop 2
	ds_read_b128 v[12:15], v79 offset:8896
	s_waitcnt lgkmcnt(0)
	v_mfma_f32_16x16x32_bf16 v[12:15], v[92:95], v[12:15], v[18:21]
	s_nop 2
	ds_read_b128 v[16:19], v79 offset:13248
	s_waitcnt lgkmcnt(0)
	v_mfma_f32_16x16x32_bf16 v[16:19], v[92:95], v[16:19], v[22:25]
	s_nop 2
	ds_read_b128 v[20:23], v79 offset:17600
	s_waitcnt lgkmcnt(0)
	v_mfma_f32_16x16x32_bf16 v[20:23], v[92:95], v[20:23], v[26:29]
	s_nop 2
	ds_read_b128 v[24:27], v79 offset:21952
	s_waitcnt lgkmcnt(0)
	v_mfma_f32_16x16x32_bf16 v[24:27], v[92:95], v[24:27], v[30:33]
	s_nop 2
	ds_read_b128 v[28:31], v79 offset:26304
	ds_read_b128 v[32:35], v79 offset:30656
	s_waitcnt lgkmcnt(1)
	v_mfma_f32_16x16x32_bf16 v[28:31], v[92:95], v[28:31], v[84:87]
	s_nop 2
	v_add_u32_e32 v84, s27, v58
	v_ashrrev_i32_e32 v85, 31, v84
	v_lshl_add_u64 v[84:85], v[84:85], 2, s[8:9]
	global_load_dwordx4 v[84:87], v[84:85], off
	s_waitcnt lgkmcnt(0)
	v_mfma_f32_16x16x32_bf16 v[32:35], v[92:95], v[32:35], v[88:91]
	s_waitcnt vmcnt(0)
	v_add_f32_e32 v4, v84, v4
	v_add_f32_e32 v8, v84, v8
	v_add_u32_e32 v88, 0xc000, v80
	ds_write2_b32 v88, v4, v8 offset1:16
	v_add_f32_e32 v4, v84, v12
	v_add_f32_e32 v8, v84, v16
	ds_write2_b32 v88, v4, v8 offset0:32 offset1:48
	v_add_f32_e32 v4, v84, v20
	v_add_f32_e32 v8, v84, v24
	ds_write2_b32 v88, v4, v8 offset0:64 offset1:80
	v_add_f32_e32 v4, v84, v28
	v_add_f32_e32 v8, v84, v32
	ds_write2_b32 v88, v4, v8 offset0:96 offset1:112
	v_add_f32_e32 v4, v85, v5
	v_add_f32_e32 v5, v85, v9
	ds_write2_b32 v88, v4, v5 offset0:132 offset1:148
	v_add_f32_e32 v4, v85, v13
	v_add_f32_e32 v5, v85, v17
	ds_write2_b32 v88, v4, v5 offset0:164 offset1:180
	v_add_f32_e32 v4, v85, v21
	v_add_f32_e32 v5, v85, v25
	ds_write2_b32 v88, v4, v5 offset0:196 offset1:212
	v_add_f32_e32 v4, v85, v29
	v_add_f32_e32 v5, v85, v33
	ds_write2_b32 v88, v4, v5 offset0:228 offset1:244
	v_add_f32_e32 v4, v86, v6
	v_add_f32_e32 v5, v86, v10
	v_add_u32_e32 v6, 0xc400, v80
	ds_write2_b32 v6, v4, v5 offset0:8 offset1:24
	v_add_f32_e32 v4, v86, v14
	v_add_f32_e32 v5, v86, v18
	ds_write2_b32 v6, v4, v5 offset0:40 offset1:56
	v_add_f32_e32 v4, v86, v22
	v_add_f32_e32 v5, v86, v26
	ds_write2_b32 v6, v4, v5 offset0:72 offset1:88
	v_add_f32_e32 v4, v86, v30
	v_add_f32_e32 v5, v86, v34
	ds_write2_b32 v6, v4, v5 offset0:104 offset1:120
	v_add_f32_e32 v4, v87, v7
	v_add_f32_e32 v5, v87, v11
	ds_write2_b32 v6, v4, v5 offset0:140 offset1:156
	v_add_f32_e32 v4, v87, v15
	v_add_f32_e32 v5, v87, v19
	ds_write2_b32 v6, v4, v5 offset0:172 offset1:188
	v_add_f32_e32 v4, v87, v23
	v_add_f32_e32 v5, v87, v27
	ds_write2_b32 v6, v4, v5 offset0:204 offset1:220
	v_add_f32_e32 v4, v87, v31
	v_add_f32_e32 v5, v87, v35
	ds_write2_b32 v6, v4, v5 offset0:236 offset1:252
	v_lshl_add_u64 v[4:5], s[14:15], 0, v[44:45]
	v_lshlrev_b64 v[4:5], 8, v[4:5]
	v_lshl_add_u64 v[4:5], v[46:47], 0, v[4:5]
	s_waitcnt lgkmcnt(0)
	s_barrier
; __device__ __forceinline__ unsigned cvt_pk_bf16(float lo, float hi) { unsigned r; asm volatile("v_cvt_pk_bf16_f32 %0, %1, %2" : "=v"(r) : "v"(lo), "v"(hi)); return r; }
; __device__ __forceinline__ float bf_lo(unsigned w) { return __uint_as_float(w << 16); }
; __device__ __forceinline__ float bf_hi(unsigned w) { return __uint_as_float(w & 0xffff0000u); }
; __global__ void __launch_bounds__(NTHR, 2) mega_fwd(Args a) {
;     ...
;                 {
;                     const int c0 = (tid & 15) * 8;
; #pragma unroll
;                     for (int i = 0; i < 4; ++i) { const int t = 32 * i + (tid >> 4);
;                         const u32x4 uw = *(const u32x4*)(PB + ((size_t)(12 + gi) * T + r0 + t) * 128 + c0);
;                         const f32x4 s0 = *(const f32x4*)(svL + t * 132 + c0), s1 = *(const f32x4*)(svL + t * 132 + c0 + 4);
;                         u32x4 w; w.x = cvt_pk_bf16(gelu_tanh(bf_lo(uw.x)) * s0[0], gelu_tanh(bf_hi(uw.x)) * s0[1]); w.y = cvt_pk_bf16(gelu_tanh(bf_lo(uw.y)) * s0[2], gelu_tanh(bf_hi(uw.y)) * s0[3]);
;                         w.z = cvt_pk_bf16(gelu_tanh(bf_lo(uw.z)) * s1[0], gelu_tanh(bf_hi(uw.z)) * s1[1]); w.w = cvt_pk_bf16(gelu_tanh(bf_lo(uw.w)) * s1[2], gelu_tanh(bf_hi(uw.w)) * s1[3]);
;                         *(u32x4*)(Y + (size_t)(r0 + t) * DM + 512 + gi * 128 + c0) = w; }
	v_mov_b64_e32 v[4:5], v[218:219]
	v_mov_b64_e32 v[6:7], v[220:221]
	v_add_u32_e32 v12, v59, v78
	ds_read_b128 v[8:11], v12 offset:49152
	ds_read_b128 v[12:15], v12 offset:49168
	s_waitcnt vmcnt(0)
	v_lshlrev_b32_e32 v16, 16, v4
	v_mul_f32_e32 v17, 0x3d372713, v16
	v_mul_f32_e32 v17, v17, v16
	v_fma_f32 v17, v17, v16, v16
	v_mul_f32_e32 v17, 0x3f4c422a, v17
	v_mul_f32_e32 v17, -2.0, v17
	v_mul_f32_e32 v17, 0x3fb8aa3b, v17
	v_exp_f32_e32 v17, v17
	v_and_b32_e32 v4, 0xffff0000, v4
	v_add_f32_e32 v17, 1.0, v17
	v_rcp_f32_e32 v17, v17
	s_nop 0
	v_mul_f32_e32 v16, v17, v16
	s_waitcnt lgkmcnt(1)
	v_mul_f32_e32 v8, v8, v16
	v_mul_f32_e32 v16, 0x3d372713, v4
	v_mul_f32_e32 v16, v16, v4
	v_fma_f32 v16, v16, v4, v4
	v_mul_f32_e32 v16, 0x3f4c422a, v16
	v_mul_f32_e32 v16, -2.0, v16
	v_mul_f32_e32 v16, 0x3fb8aa3b, v16
	v_exp_f32_e32 v16, v16
	s_nop 0
	v_add_f32_e32 v16, 1.0, v16
	v_rcp_f32_e32 v16, v16
	s_nop 0
	v_mul_f32_e32 v4, v16, v4
	v_mul_f32_e32 v4, v9, v4
	v_cvt_pk_bf16_f32 v4, v8, v4
	v_lshlrev_b32_e32 v8, 16, v5
	v_mul_f32_e32 v9, 0x3d372713, v8
	v_mul_f32_e32 v9, v9, v8
	v_fma_f32 v9, v9, v8, v8
	v_mul_f32_e32 v9, 0x3f4c422a, v9
	v_mul_f32_e32 v9, -2.0, v9
	v_mul_f32_e32 v9, 0x3fb8aa3b, v9
	v_exp_f32_e32 v9, v9
	v_and_b32_e32 v5, 0xffff0000, v5
	v_add_f32_e32 v9, 1.0, v9
	v_rcp_f32_e32 v9, v9
	s_nop 0
	v_mul_f32_e32 v8, v9, v8
	v_mul_f32_e32 v9, 0x3d372713, v5
	v_mul_f32_e32 v9, v9, v5
	v_fma_f32 v9, v9, v5, v5
	v_mul_f32_e32 v9, 0x3f4c422a, v9
	v_mul_f32_e32 v9, -2.0, v9
	v_mul_f32_e32 v9, 0x3fb8aa3b, v9
	v_exp_f32_e32 v9, v9
	v_mul_f32_e32 v8, v10, v8
	v_add_f32_e32 v9, 1.0, v9
	v_rcp_f32_e32 v9, v9
	s_nop 0
	v_mul_f32_e32 v5, v9, v5
	v_mul_f32_e32 v5, v11, v5
	v_cvt_pk_bf16_f32 v5, v8, v5
	v_lshlrev_b32_e32 v8, 16, v6
	v_mul_f32_e32 v9, 0x3d372713, v8
	v_mul_f32_e32 v9, v9, v8
	v_fma_f32 v9, v9, v8, v8
	v_mul_f32_e32 v9, 0x3f4c422a, v9
	v_mul_f32_e32 v9, -2.0, v9
	v_mul_f32_e32 v9, 0x3fb8aa3b, v9
	v_exp_f32_e32 v9, v9
	v_and_b32_e32 v6, 0xffff0000, v6
	v_add_f32_e32 v9, 1.0, v9
	v_rcp_f32_e32 v9, v9
	s_nop 0
	v_mul_f32_e32 v8, v9, v8
	v_mul_f32_e32 v9, 0x3d372713, v6
	v_mul_f32_e32 v9, v9, v6
	v_fma_f32 v9, v9, v6, v6
	v_mul_f32_e32 v9, 0x3f4c422a, v9
	v_mul_f32_e32 v9, -2.0, v9
	v_mul_f32_e32 v9, 0x3fb8aa3b, v9
	v_exp_f32_e32 v9, v9
	s_waitcnt lgkmcnt(0)
	v_mul_f32_e32 v8, v12, v8
	v_add_f32_e32 v9, 1.0, v9
	v_rcp_f32_e32 v9, v9
	s_nop 0
	v_mul_f32_e32 v6, v9, v6
	v_mul_f32_e32 v6, v13, v6
	v_cvt_pk_bf16_f32 v6, v8, v6
	v_lshlrev_b32_e32 v8, 16, v7
	v_mul_f32_e32 v9, 0x3d372713, v8
	v_mul_f32_e32 v9, v9, v8
	v_fma_f32 v9, v9, v8, v8
	v_mul_f32_e32 v9, 0x3f4c422a, v9
	v_mul_f32_e32 v9, -2.0, v9
	v_mul_f32_e32 v9, 0x3fb8aa3b, v9
	v_exp_f32_e32 v9, v9
	v_and_b32_e32 v7, 0xffff0000, v7
	v_add_f32_e32 v9, 1.0, v9
	v_rcp_f32_e32 v9, v9
	s_nop 0
	v_mul_f32_e32 v8, v9, v8
	v_mul_f32_e32 v9, 0x3d372713, v7
	v_mul_f32_e32 v9, v9, v7
	v_fma_f32 v9, v9, v7, v7
	v_mul_f32_e32 v9, 0x3f4c422a, v9
	v_mul_f32_e32 v9, -2.0, v9
	v_mul_f32_e32 v9, 0x3fb8aa3b, v9
	v_exp_f32_e32 v9, v9
	v_mul_f32_e32 v8, v14, v8
	v_add_f32_e32 v9, 1.0, v9
	v_rcp_f32_e32 v9, v9
	s_nop 0
	v_mul_f32_e32 v7, v9, v7
	v_mul_f32_e32 v7, v15, v7
	v_cvt_pk_bf16_f32 v7, v8, v7
	v_add_u32_e32 v8, s23, v44
	v_ashrrev_i32_e32 v9, 31, v8
	v_lshlrev_b64 v[8:9], 12, v[8:9]
	v_lshl_add_u64 v[8:9], s[0:1], 0, v[8:9]
	v_lshl_add_u64 v[8:9], v[8:9], 0, s[30:31]
	v_lshl_add_u64 v[8:9], v[8:9], 0, v[2:3]
	v_add_co_u32_e32 v8, vcc, s49, v8
	s_nop 1
	v_addc_co_u32_e32 v9, vcc, 0, v9, vcc
	global_store_dwordx4 v[8:9], v[4:7], off offset:1024
	s_nop 1
	v_lshl_add_u64 v[4:5], s[14:15], 0, v[48:49]
	v_lshlrev_b64 v[4:5], 8, v[4:5]
	v_lshl_add_u64 v[4:5], v[46:47], 0, v[4:5]
	v_mov_b64_e32 v[4:5], v[222:223]
	v_mov_b64_e32 v[6:7], v[224:225]
	ds_read_b128 v[8:11], v81 offset:49152
	ds_read_b128 v[12:15], v81 offset:49168
	v_lshlrev_b32_e32 v16, 16, v4
	v_mul_f32_e32 v17, 0x3d372713, v16
	v_mul_f32_e32 v17, v17, v16
	v_fma_f32 v17, v17, v16, v16
	v_mul_f32_e32 v17, 0x3f4c422a, v17
	v_mul_f32_e32 v17, -2.0, v17
	v_mul_f32_e32 v17, 0x3fb8aa3b, v17
	v_exp_f32_e32 v17, v17
	v_and_b32_e32 v4, 0xffff0000, v4
	v_add_f32_e32 v17, 1.0, v17
	v_rcp_f32_e32 v17, v17
	s_nop 0
	v_mul_f32_e32 v16, v17, v16
	s_waitcnt lgkmcnt(1)
	v_mul_f32_e32 v8, v8, v16
	v_mul_f32_e32 v16, 0x3d372713, v4
	v_mul_f32_e32 v16, v16, v4
	v_fma_f32 v16, v16, v4, v4
	v_mul_f32_e32 v16, 0x3f4c422a, v16
	v_mul_f32_e32 v16, -2.0, v16
	v_mul_f32_e32 v16, 0x3fb8aa3b, v16
	v_exp_f32_e32 v16, v16
	s_nop 0
	v_add_f32_e32 v16, 1.0, v16
	v_rcp_f32_e32 v16, v16
	s_nop 0
	v_mul_f32_e32 v4, v16, v4
	v_mul_f32_e32 v4, v9, v4
	v_cvt_pk_bf16_f32 v4, v8, v4
	v_lshlrev_b32_e32 v8, 16, v5
	v_mul_f32_e32 v9, 0x3d372713, v8
	v_mul_f32_e32 v9, v9, v8
	v_fma_f32 v9, v9, v8, v8
	v_mul_f32_e32 v9, 0x3f4c422a, v9
	v_mul_f32_e32 v9, -2.0, v9
	v_mul_f32_e32 v9, 0x3fb8aa3b, v9
	v_exp_f32_e32 v9, v9
	v_and_b32_e32 v5, 0xffff0000, v5
	v_add_f32_e32 v9, 1.0, v9
	v_rcp_f32_e32 v9, v9
	s_nop 0
	v_mul_f32_e32 v8, v9, v8
	v_mul_f32_e32 v9, 0x3d372713, v5
	v_mul_f32_e32 v9, v9, v5
	v_fma_f32 v9, v9, v5, v5
	v_mul_f32_e32 v9, 0x3f4c422a, v9
	v_mul_f32_e32 v9, -2.0, v9
	v_mul_f32_e32 v9, 0x3fb8aa3b, v9
	v_exp_f32_e32 v9, v9
	v_mul_f32_e32 v8, v10, v8
	v_add_f32_e32 v9, 1.0, v9
	v_rcp_f32_e32 v9, v9
	s_nop 0
	v_mul_f32_e32 v5, v9, v5
	v_mul_f32_e32 v5, v11, v5
	v_cvt_pk_bf16_f32 v5, v8, v5
	v_lshlrev_b32_e32 v8, 16, v6
	v_mul_f32_e32 v9, 0x3d372713, v8
	v_mul_f32_e32 v9, v9, v8
	v_fma_f32 v9, v9, v8, v8
	v_mul_f32_e32 v9, 0x3f4c422a, v9
	v_mul_f32_e32 v9, -2.0, v9
	v_mul_f32_e32 v9, 0x3fb8aa3b, v9
	v_exp_f32_e32 v9, v9
	v_and_b32_e32 v6, 0xffff0000, v6
	v_add_f32_e32 v9, 1.0, v9
	v_rcp_f32_e32 v9, v9
	s_nop 0
	v_mul_f32_e32 v8, v9, v8
	v_mul_f32_e32 v9, 0x3d372713, v6
	v_mul_f32_e32 v9, v9, v6
	v_fma_f32 v9, v9, v6, v6
	v_mul_f32_e32 v9, 0x3f4c422a, v9
	v_mul_f32_e32 v9, -2.0, v9
	v_mul_f32_e32 v9, 0x3fb8aa3b, v9
	v_exp_f32_e32 v9, v9
	s_waitcnt lgkmcnt(0)
; __device__ __forceinline__ unsigned cvt_pk_bf16(float lo, float hi) { unsigned r; asm volatile("v_cvt_pk_bf16_f32 %0, %1, %2" : "=v"(r) : "v"(lo), "v"(hi)); return r; }
; __device__ __forceinline__ float bf_lo(unsigned w) { return __uint_as_float(w << 16); }
; __device__ __forceinline__ float bf_hi(unsigned w) { return __uint_as_float(w & 0xffff0000u); }
; __global__ void __launch_bounds__(NTHR, 2) mega_fwd(Args a) {
;     ...
;                 {
;                     const int c0 = (tid & 15) * 8;
; #pragma unroll
;                     for (int i = 0; i < 4; ++i) { const int t = 32 * i + (tid >> 4);
;                         const u32x4 uw = *(const u32x4*)(PB + ((size_t)(12 + gi) * T + r0 + t) * 128 + c0);
;                         const f32x4 s0 = *(const f32x4*)(svL + t * 132 + c0), s1 = *(const f32x4*)(svL + t * 132 + c0 + 4);
;                         u32x4 w; w.x = cvt_pk_bf16(gelu_tanh(bf_lo(uw.x)) * s0[0], gelu_tanh(bf_hi(uw.x)) * s0[1]); w.y = cvt_pk_bf16(gelu_tanh(bf_lo(uw.y)) * s0[2], gelu_tanh(bf_hi(uw.y)) * s0[3]);
;                         w.z = cvt_pk_bf16(gelu_tanh(bf_lo(uw.z)) * s1[0], gelu_tanh(bf_hi(uw.z)) * s1[1]); w.w = cvt_pk_bf16(gelu_tanh(bf_lo(uw.w)) * s1[2], gelu_tanh(bf_hi(uw.w)) * s1[3]);
;                         *(u32x4*)(Y + (size_t)(r0 + t) * DM + 512 + gi * 128 + c0) = w; }
	v_mul_f32_e32 v8, v12, v8
	v_add_f32_e32 v9, 1.0, v9
	v_rcp_f32_e32 v9, v9
	s_nop 0
	v_mul_f32_e32 v6, v9, v6
	v_mul_f32_e32 v6, v13, v6
	v_cvt_pk_bf16_f32 v6, v8, v6
	v_lshlrev_b32_e32 v8, 16, v7
	v_mul_f32_e32 v9, 0x3d372713, v8
	v_mul_f32_e32 v9, v9, v8
	v_fma_f32 v9, v9, v8, v8
	v_mul_f32_e32 v9, 0x3f4c422a, v9
	v_mul_f32_e32 v9, -2.0, v9
	v_mul_f32_e32 v9, 0x3fb8aa3b, v9
	v_exp_f32_e32 v9, v9
	v_and_b32_e32 v7, 0xffff0000, v7
	v_add_f32_e32 v9, 1.0, v9
	v_rcp_f32_e32 v9, v9
	s_nop 0
	v_mul_f32_e32 v8, v9, v8
	v_mul_f32_e32 v9, 0x3d372713, v7
	v_mul_f32_e32 v9, v9, v7
	v_fma_f32 v9, v9, v7, v7
	v_mul_f32_e32 v9, 0x3f4c422a, v9
	v_mul_f32_e32 v9, -2.0, v9
	v_mul_f32_e32 v9, 0x3fb8aa3b, v9
	v_exp_f32_e32 v9, v9
	v_mul_f32_e32 v8, v14, v8
	v_add_f32_e32 v9, 1.0, v9
	v_rcp_f32_e32 v9, v9
	s_nop 0
	v_mul_f32_e32 v7, v9, v7
	v_mul_f32_e32 v7, v15, v7
	v_cvt_pk_bf16_f32 v7, v8, v7
	v_add_u32_e32 v8, s23, v48
	v_ashrrev_i32_e32 v9, 31, v8
	v_lshlrev_b64 v[8:9], 12, v[8:9]
	v_lshl_add_u64 v[8:9], s[0:1], 0, v[8:9]
	v_lshl_add_u64 v[8:9], v[8:9], 0, s[30:31]
	v_lshl_add_u64 v[8:9], v[8:9], 0, v[2:3]
	v_add_co_u32_e32 v8, vcc, s49, v8
	s_nop 1
	v_addc_co_u32_e32 v9, vcc, 0, v9, vcc
	global_store_dwordx4 v[8:9], v[4:7], off offset:1024
	s_nop 1
	v_lshl_add_u64 v[4:5], s[14:15], 0, v[50:51]
	v_lshlrev_b64 v[4:5], 8, v[4:5]
	v_lshl_add_u64 v[4:5], v[46:47], 0, v[4:5]
	v_mov_b64_e32 v[4:5], v[226:227]
	v_mov_b64_e32 v[6:7], v[228:229]
	ds_read_b128 v[8:11], v82 offset:49152
	ds_read_b128 v[12:15], v82 offset:49168
	v_lshlrev_b32_e32 v16, 16, v4
	v_mul_f32_e32 v17, 0x3d372713, v16
	v_mul_f32_e32 v17, v17, v16
	v_fma_f32 v17, v17, v16, v16
	v_mul_f32_e32 v17, 0x3f4c422a, v17
	v_mul_f32_e32 v17, -2.0, v17
	v_mul_f32_e32 v17, 0x3fb8aa3b, v17
	v_exp_f32_e32 v17, v17
	v_and_b32_e32 v4, 0xffff0000, v4
	v_add_f32_e32 v17, 1.0, v17
	v_rcp_f32_e32 v17, v17
	s_nop 0
	v_mul_f32_e32 v16, v17, v16
	s_waitcnt lgkmcnt(1)
	v_mul_f32_e32 v8, v8, v16
	v_mul_f32_e32 v16, 0x3d372713, v4
	v_mul_f32_e32 v16, v16, v4
	v_fma_f32 v16, v16, v4, v4
	v_mul_f32_e32 v16, 0x3f4c422a, v16
	v_mul_f32_e32 v16, -2.0, v16
	v_mul_f32_e32 v16, 0x3fb8aa3b, v16
	v_exp_f32_e32 v16, v16
	s_nop 0
	v_add_f32_e32 v16, 1.0, v16
	v_rcp_f32_e32 v16, v16
	s_nop 0
	v_mul_f32_e32 v4, v16, v4
	v_mul_f32_e32 v4, v9, v4
	v_cvt_pk_bf16_f32 v4, v8, v4
	v_lshlrev_b32_e32 v8, 16, v5
	v_mul_f32_e32 v9, 0x3d372713, v8
	v_mul_f32_e32 v9, v9, v8
	v_fma_f32 v9, v9, v8, v8
	v_mul_f32_e32 v9, 0x3f4c422a, v9
	v_mul_f32_e32 v9, -2.0, v9
	v_mul_f32_e32 v9, 0x3fb8aa3b, v9
	v_exp_f32_e32 v9, v9
	v_and_b32_e32 v5, 0xffff0000, v5
	v_add_f32_e32 v9, 1.0, v9
	v_rcp_f32_e32 v9, v9
	s_nop 0
	v_mul_f32_e32 v8, v9, v8
	v_mul_f32_e32 v9, 0x3d372713, v5
	v_mul_f32_e32 v9, v9, v5
	v_fma_f32 v9, v9, v5, v5
	v_mul_f32_e32 v9, 0x3f4c422a, v9
	v_mul_f32_e32 v9, -2.0, v9
	v_mul_f32_e32 v9, 0x3fb8aa3b, v9
	v_exp_f32_e32 v9, v9
	v_mul_f32_e32 v8, v10, v8
	v_add_f32_e32 v9, 1.0, v9
	v_rcp_f32_e32 v9, v9
	s_nop 0
	v_mul_f32_e32 v5, v9, v5
	v_mul_f32_e32 v5, v11, v5
	v_cvt_pk_bf16_f32 v5, v8, v5
	v_lshlrev_b32_e32 v8, 16, v6
	v_mul_f32_e32 v9, 0x3d372713, v8
	v_mul_f32_e32 v9, v9, v8
	v_fma_f32 v9, v9, v8, v8
	v_mul_f32_e32 v9, 0x3f4c422a, v9
	v_mul_f32_e32 v9, -2.0, v9
	v_mul_f32_e32 v9, 0x3fb8aa3b, v9
	v_exp_f32_e32 v9, v9
	v_and_b32_e32 v6, 0xffff0000, v6
	v_add_f32_e32 v9, 1.0, v9
	v_rcp_f32_e32 v9, v9
	s_nop 0
	v_mul_f32_e32 v8, v9, v8
	v_mul_f32_e32 v9, 0x3d372713, v6
	v_mul_f32_e32 v9, v9, v6
	v_fma_f32 v9, v9, v6, v6
	v_mul_f32_e32 v9, 0x3f4c422a, v9
	v_mul_f32_e32 v9, -2.0, v9
	v_mul_f32_e32 v9, 0x3fb8aa3b, v9
	v_exp_f32_e32 v9, v9
	s_waitcnt lgkmcnt(0)
	v_mul_f32_e32 v8, v12, v8
	v_add_f32_e32 v9, 1.0, v9
	v_rcp_f32_e32 v9, v9
	s_nop 0
	v_mul_f32_e32 v6, v9, v6
	v_mul_f32_e32 v6, v13, v6
	v_cvt_pk_bf16_f32 v6, v8, v6
	v_lshlrev_b32_e32 v8, 16, v7
	v_mul_f32_e32 v9, 0x3d372713, v8
	v_mul_f32_e32 v9, v9, v8
	v_fma_f32 v9, v9, v8, v8
	v_mul_f32_e32 v9, 0x3f4c422a, v9
	v_mul_f32_e32 v9, -2.0, v9
	v_mul_f32_e32 v9, 0x3fb8aa3b, v9
	v_exp_f32_e32 v9, v9
	v_and_b32_e32 v7, 0xffff0000, v7
	v_add_f32_e32 v9, 1.0, v9
	v_rcp_f32_e32 v9, v9
	s_nop 0
	v_mul_f32_e32 v8, v9, v8
	v_mul_f32_e32 v9, 0x3d372713, v7
	v_mul_f32_e32 v9, v9, v7
	v_fma_f32 v9, v9, v7, v7
	v_mul_f32_e32 v9, 0x3f4c422a, v9
	v_mul_f32_e32 v9, -2.0, v9
	v_mul_f32_e32 v9, 0x3fb8aa3b, v9
	v_exp_f32_e32 v9, v9
	v_mul_f32_e32 v8, v14, v8
	v_add_f32_e32 v9, 1.0, v9
	v_rcp_f32_e32 v9, v9
	s_nop 0
	v_mul_f32_e32 v7, v9, v7
	v_mul_f32_e32 v7, v15, v7
	v_cvt_pk_bf16_f32 v7, v8, v7
	v_add_u32_e32 v8, s23, v50
	v_ashrrev_i32_e32 v9, 31, v8
	v_lshlrev_b64 v[8:9], 12, v[8:9]
	v_lshl_add_u64 v[8:9], s[0:1], 0, v[8:9]
	v_lshl_add_u64 v[8:9], v[8:9], 0, s[30:31]
	v_lshl_add_u64 v[8:9], v[8:9], 0, v[2:3]
	v_add_co_u32_e32 v8, vcc, s49, v8
	s_nop 1
	v_addc_co_u32_e32 v9, vcc, 0, v9, vcc
	global_store_dwordx4 v[8:9], v[4:7], off offset:1024
	s_nop 1
	v_lshl_add_u64 v[4:5], s[14:15], 0, v[52:53]
	v_lshlrev_b64 v[4:5], 8, v[4:5]
	v_lshl_add_u64 v[4:5], v[46:47], 0, v[4:5]
	v_mov_b64_e32 v[4:5], v[230:231]
	v_mov_b64_e32 v[6:7], v[232:233]
	ds_read_b128 v[8:11], v83 offset:49152
	ds_read_b128 v[12:15], v83 offset:49168
	v_lshlrev_b32_e32 v16, 16, v4
	v_mul_f32_e32 v17, 0x3d372713, v16
	v_mul_f32_e32 v17, v17, v16
	v_fma_f32 v17, v17, v16, v16
	v_mul_f32_e32 v17, 0x3f4c422a, v17
	v_mul_f32_e32 v17, -2.0, v17
	v_mul_f32_e32 v17, 0x3fb8aa3b, v17
	v_exp_f32_e32 v17, v17
	v_and_b32_e32 v4, 0xffff0000, v4
	v_add_f32_e32 v17, 1.0, v17
	v_rcp_f32_e32 v17, v17
	s_nop 0
	v_mul_f32_e32 v16, v17, v16
	s_waitcnt lgkmcnt(1)
; __device__ __forceinline__ unsigned cvt_pk_bf16(float lo, float hi) { unsigned r; asm volatile("v_cvt_pk_bf16_f32 %0, %1, %2" : "=v"(r) : "v"(lo), "v"(hi)); return r; }
; __device__ __forceinline__ float bf_lo(unsigned w) { return __uint_as_float(w << 16); }
; __device__ __forceinline__ float bf_hi(unsigned w) { return __uint_as_float(w & 0xffff0000u); }
; __global__ void __launch_bounds__(NTHR, 2) mega_fwd(Args a) {
;     ...
;             for (int un = cu; un < (T / 128) * 4; un += G) {
;                 const int ch = un >> 2, gi = un & 3, r0 = ch * 128;
;                 if (tid < 128) {
;                     const float s1 = gstat[2 * (r0 + tid)], s2 = gstat[2 * (r0 + tid) + 1];
;                     const float mean = s1 * (1.f / 512.f), var = fmaxf(s2 * (1.f / 512.f) - mean * mean, 0.f);
;                     st[2 * tid] = mean; st[2 * tid + 1] = rsqrtf(var + LN_EPS); }
;                 __syncthreads();
;                 {
;                     const int tok = tid >> 2, cq = (tid & 3) * 32; const float mean = st[2 * tok], rstd = st[2 * tok + 1];
;                     const bf16_t* vp = PB + ((size_t)(16 + gi) * T + r0 + tok) * 128 + cq;
; #pragma unroll
;                     for (int i = 0; i < 4; ++i) { const u32x4 w = *(const u32x4*)(vp + 8 * i);
;     ...
;                 {
;                     const int c0 = (tid & 15) * 8;
; #pragma unroll
;                     for (int i = 0; i < 4; ++i) { const int t = 32 * i + (tid >> 4);
;                         const u32x4 uw = *(const u32x4*)(PB + ((size_t)(12 + gi) * T + r0 + t) * 128 + c0);
;                         const f32x4 s0 = *(const f32x4*)(svL + t * 132 + c0), s1 = *(const f32x4*)(svL + t * 132 + c0 + 4);
;                         u32x4 w; w.x = cvt_pk_bf16(gelu_tanh(bf_lo(uw.x)) * s0[0], gelu_tanh(bf_hi(uw.x)) * s0[1]); w.y = cvt_pk_bf16(gelu_tanh(bf_lo(uw.y)) * s0[2], gelu_tanh(bf_hi(uw.y)) * s0[3]);
;                         w.z = cvt_pk_bf16(gelu_tanh(bf_lo(uw.z)) * s1[0], gelu_tanh(bf_hi(uw.z)) * s1[1]); w.w = cvt_pk_bf16(gelu_tanh(bf_lo(uw.w)) * s1[2], gelu_tanh(bf_hi(uw.w)) * s1[3]);
;                         *(u32x4*)(Y + (size_t)(r0 + t) * DM + 512 + gi * 128 + c0) = w; }
;                 }
;                 __syncthreads();
	v_mul_f32_e32 v8, v8, v16
	v_mul_f32_e32 v16, 0x3d372713, v4
	v_mul_f32_e32 v16, v16, v4
	v_fma_f32 v16, v16, v4, v4
	v_mul_f32_e32 v16, 0x3f4c422a, v16
	v_mul_f32_e32 v16, -2.0, v16
	v_mul_f32_e32 v16, 0x3fb8aa3b, v16
	v_exp_f32_e32 v16, v16
	s_nop 0
	v_add_f32_e32 v16, 1.0, v16
	v_rcp_f32_e32 v16, v16
	s_nop 0
	v_mul_f32_e32 v4, v16, v4
	v_mul_f32_e32 v4, v9, v4
	v_cvt_pk_bf16_f32 v4, v8, v4
	v_lshlrev_b32_e32 v8, 16, v5
	v_mul_f32_e32 v9, 0x3d372713, v8
	v_mul_f32_e32 v9, v9, v8
	v_fma_f32 v9, v9, v8, v8
	v_mul_f32_e32 v9, 0x3f4c422a, v9
	v_mul_f32_e32 v9, -2.0, v9
	v_mul_f32_e32 v9, 0x3fb8aa3b, v9
	v_exp_f32_e32 v9, v9
	v_and_b32_e32 v5, 0xffff0000, v5
	v_add_f32_e32 v9, 1.0, v9
	v_rcp_f32_e32 v9, v9
	s_nop 0
	v_mul_f32_e32 v8, v9, v8
	v_mul_f32_e32 v9, 0x3d372713, v5
	v_mul_f32_e32 v9, v9, v5
	v_fma_f32 v9, v9, v5, v5
	v_mul_f32_e32 v9, 0x3f4c422a, v9
	v_mul_f32_e32 v9, -2.0, v9
	v_mul_f32_e32 v9, 0x3fb8aa3b, v9
	v_exp_f32_e32 v9, v9
	v_mul_f32_e32 v8, v10, v8
	v_add_f32_e32 v9, 1.0, v9
	v_rcp_f32_e32 v9, v9
	s_nop 0
	v_mul_f32_e32 v5, v9, v5
	v_mul_f32_e32 v5, v11, v5
	v_cvt_pk_bf16_f32 v5, v8, v5
	v_lshlrev_b32_e32 v8, 16, v6
	v_mul_f32_e32 v9, 0x3d372713, v8
	v_mul_f32_e32 v9, v9, v8
	v_fma_f32 v9, v9, v8, v8
	v_mul_f32_e32 v9, 0x3f4c422a, v9
	v_mul_f32_e32 v9, -2.0, v9
	v_mul_f32_e32 v9, 0x3fb8aa3b, v9
	v_exp_f32_e32 v9, v9
	v_and_b32_e32 v6, 0xffff0000, v6
	v_add_f32_e32 v9, 1.0, v9
	v_rcp_f32_e32 v9, v9
	s_nop 0
	v_mul_f32_e32 v8, v9, v8
	v_mul_f32_e32 v9, 0x3d372713, v6
	v_mul_f32_e32 v9, v9, v6
	v_fma_f32 v9, v9, v6, v6
	v_mul_f32_e32 v9, 0x3f4c422a, v9
	v_mul_f32_e32 v9, -2.0, v9
	v_mul_f32_e32 v9, 0x3fb8aa3b, v9
	v_exp_f32_e32 v9, v9
	s_waitcnt lgkmcnt(0)
	v_mul_f32_e32 v8, v12, v8
	v_add_f32_e32 v9, 1.0, v9
	v_rcp_f32_e32 v9, v9
	s_nop 0
	v_mul_f32_e32 v6, v9, v6
	v_mul_f32_e32 v6, v13, v6
	v_cvt_pk_bf16_f32 v6, v8, v6
	v_lshlrev_b32_e32 v8, 16, v7
	v_mul_f32_e32 v9, 0x3d372713, v8
	v_mul_f32_e32 v9, v9, v8
	v_fma_f32 v9, v9, v8, v8
	v_mul_f32_e32 v9, 0x3f4c422a, v9
	v_mul_f32_e32 v9, -2.0, v9
	v_mul_f32_e32 v9, 0x3fb8aa3b, v9
	v_exp_f32_e32 v9, v9
	v_and_b32_e32 v7, 0xffff0000, v7
	v_add_f32_e32 v9, 1.0, v9
	v_rcp_f32_e32 v9, v9
	s_nop 0
	v_mul_f32_e32 v8, v9, v8
	v_mul_f32_e32 v9, 0x3d372713, v7
	v_mul_f32_e32 v9, v9, v7
	v_fma_f32 v9, v9, v7, v7
	v_mul_f32_e32 v9, 0x3f4c422a, v9
	v_mul_f32_e32 v9, -2.0, v9
	v_mul_f32_e32 v9, 0x3fb8aa3b, v9
	v_exp_f32_e32 v9, v9
	v_mul_f32_e32 v8, v14, v8
	v_add_f32_e32 v9, 1.0, v9
	v_rcp_f32_e32 v9, v9
	s_nop 0
	v_mul_f32_e32 v7, v9, v7
	v_mul_f32_e32 v7, v15, v7
	v_cvt_pk_bf16_f32 v7, v8, v7
	v_add_u32_e32 v8, s23, v52
	v_ashrrev_i32_e32 v9, 31, v8
	v_lshlrev_b64 v[8:9], 12, v[8:9]
	v_lshl_add_u64 v[8:9], s[0:1], 0, v[8:9]
	v_lshl_add_u64 v[8:9], v[8:9], 0, s[30:31]
	v_lshl_add_u64 v[8:9], v[8:9], 0, v[2:3]
	v_add_co_u32_e32 v8, vcc, 0x28000000, v8
	s_nop 1
	v_addc_co_u32_e32 v9, vcc, 0, v9, vcc
	global_store_dwordx4 v[8:9], v[4:7], off offset:1024
	s_barrier
	s_cbranch_scc1 .LBB0_521
.LBB0_519:
	s_and_b32 s23, s17, 0xffffff80
	s_and_b32 s26, s22, 3
	s_lshl_b32 s14, s26, 14
	s_or_b32 s10, s14, 0x40000
	s_ashr_i32 s15, s23, 31
	s_add_u32 s34, s10, s23
	s_addc_u32 s35, 0, s15
	v_lshl_add_u64 v[234:235], s[34:35], 0, v[36:37]
	v_lshlrev_b64 v[234:235], 8, v[234:235]
	v_lshl_add_u64 v[234:235], v[38:39], 0, v[234:235]
	global_load_dwordx4 v[96:99], v[234:235], off
	global_load_dwordx4 v[100:103], v[234:235], off offset:16
	global_load_dwordx4 v[104:107], v[234:235], off offset:32
	global_load_dwordx4 v[108:111], v[234:235], off offset:48
	s_lshl_b32 s11, s26, 7
	v_or_b32_e32 v112, s11, v56
	v_lshlrev_b32_e32 v112, 2, v112
	global_load_dwordx4 v[116:119], v112, s[4:5]
	global_load_dwordx4 v[120:123], v112, s[4:5] offset:16
	global_load_dwordx4 v[124:127], v112, s[4:5] offset:32
	global_load_dwordx4 v[128:131], v112, s[4:5] offset:48
	global_load_dwordx4 v[132:135], v112, s[4:5] offset:64
	global_load_dwordx4 v[136:139], v112, s[4:5] offset:80
	global_load_dwordx4 v[140:143], v112, s[4:5] offset:96
	global_load_dwordx4 v[144:147], v112, s[4:5] offset:112
	global_load_dwordx4 v[148:151], v112, s[6:7]
	global_load_dwordx4 v[152:155], v112, s[6:7] offset:16
	global_load_dwordx4 v[156:159], v112, s[6:7] offset:32
	global_load_dwordx4 v[160:163], v112, s[6:7] offset:48
	global_load_dwordx4 v[164:167], v112, s[6:7] offset:64
	global_load_dwordx4 v[168:171], v112, s[6:7] offset:80
	global_load_dwordx4 v[172:175], v112, s[6:7] offset:96
	global_load_dwordx4 v[176:179], v112, s[6:7] offset:112
	s_and_saveexec_b64 s[14:15], s[2:3]
	s_cbranch_execz .LBB0_518
	v_add_lshl_u32 v4, s23, v54, 1
	v_ashrrev_i32_e32 v5, 31, v4
	v_lshl_add_u64 v[4:5], v[4:5], 2, s[82:83]
	global_load_dwordx2 v[4:5], v[4:5], off
	s_mov_b32 s26, 0x3b000000
	s_waitcnt vmcnt(0)
	v_pk_mul_f32 v[4:5], v[4:5], s[26:27] op_sel_hi:[1,0]
	s_nop 0
	v_fma_f32 v5, -v4, v4, v5
	v_max_f32_e32 v5, 0, v5
	v_add_f32_e32 v5, 0x3727c5ac, v5
	v_mul_f32_e32 v6, 0x4b800000, v5
	v_cmp_gt_f32_e32 vcc, s45, v5
	s_nop 1
	v_cndmask_b32_e32 v5, v5, v6, vcc
	v_rsq_f32_e32 v5, v5
	v_add_u32_e32 v6, 0, v55
	v_mul_f32_e32 v7, 0x45800000, v5
	v_cndmask_b32_e32 v5, v5, v7, vcc
	ds_write_b64 v6, v[4:5] offset:40960
	s_branch .LBB0_518
